# static s_setprio 1 for waves 4-7 (younger half) during attention phases 3-4
# baseline (speedup 1.0000x reference)
.LBB0_757:
	v_readfirstlane_b32 s98, v240
	s_lshr_b32 s98, s98, 6
	s_cmp_ge_u32 s98, 4
	s_cbranch_scc0 .Lprio3_done
	s_setprio 1

.LBB0_976:
	s_setprio 0
	s_cmpk_lt_i32 s91, 0x208
	v_mov_b32_e32 v9, v198
	s_barrier
	s_cbranch_scc0 .LBB0_988
	v_lshlrev_b32_e32 v11, 4, v9
	v_add_u32_e32 v0, s86, v11
	v_add_u32_e32 v1, 0x2000, v0
	v_ashrrev_i32_e32 v2, 31, v1
	v_lshrrev_b32_e32 v2, 22, v2
	v_add_u32_e32 v2, v1, v2
	v_ashrrev_i32_e32 v8, 10, v2
	v_mul_i32_i24_e32 v3, 0x400, v8
	v_sub_u32_e32 v1, v1, v3
	v_lshrrev_b32_e32 v3, 4, v1
	v_bitop3_b32 v1, v3, v1, 32 bitop3:0x6c
	v_ashrrev_i32_e32 v3, 31, v1
	v_lshrrev_b32_e32 v3, 26, v3
	v_add_u32_e32 v3, v1, v3
	v_ashrrev_i32_e32 v10, 6, v3
	v_and_b32_e32 v3, 0xffc0, v3
	v_sub_u32_e32 v1, v1, v3
	v_lshrrev_b16_e32 v3, 7, v1
	v_and_b32_e32 v3, 1, v3
	v_add_u16_e32 v1, v1, v3
	v_mov_b32_e32 v3, 1
	v_lshlrev_b32_e32 v2, 5, v8
	v_ashrrev_i16_sdwa v1, v3, sext(v1) dst_sel:DWORD dst_unused:UNUSED_PAD src0_sel:DWORD src1_sel:BYTE_0
	v_and_b32_e32 v2, 32, v2
	v_bfe_i32 v12, v1, 0, 16
	v_add_u32_e32 v1, v2, v12
	v_lshlrev_b32_e32 v2, 3, v8
	v_and_b32_e32 v2, 0x1ffff0, v2
	v_add_lshl_u32 v2, v10, v2, 11
	v_lshl_add_u32 v128, v1, 1, v2
	v_ashrrev_i32_e32 v1, 31, v0
	v_readlane_b32 s0, v252, 40
	v_lshrrev_b32_e32 v1, 22, v1
	v_readlane_b32 s1, v252, 41
	v_add_u32_e32 v1, v0, v1
	s_movk_i32 s26, 0x42
	s_and_b64 s[0:1], s[0:1], exec
	v_ashrrev_i32_e32 v13, 10, v1
	s_cselect_b32 s0, s26, 0x41
	v_readlane_b32 s1, v252, 39
	v_mul_i32_i24_e32 v2, 0x400, v13
	s_mul_i32 s0, s1, s0
	v_readlane_b32 s1, v252, 38
	v_sub_u32_e32 v0, v0, v2
	s_add_i32 s0, s0, s1
	v_lshrrev_b32_e32 v2, 4, v0
	s_ashr_i32 s1, s0, 31
	v_bitop3_b32 v0, v2, v0, 32 bitop3:0x6c
	s_lshr_b32 s1, s1, 27
	v_ashrrev_i32_e32 v2, 31, v0
	s_add_i32 s1, s0, s1
	v_lshrrev_b32_e32 v2, 26, v2
	s_ashr_i32 s2, s1, 5
	v_add_u32_e32 v2, v0, v2
	s_lshl_b32 s2, s2, 3
	v_ashrrev_i32_e32 v14, 6, v2
	v_and_b32_e32 v2, 0xc0, v2
	s_sub_i32 s3, 0x82, s2
	v_sub_u32_e32 v0, v0, v2
	s_min_u32 s3, s3, 8
	s_andn2_b32 s1, s1, 31
	v_lshlrev_b32_e32 v1, 5, v13
	v_ashrrev_i16_sdwa v0, v3, sext(v0) dst_sel:DWORD dst_unused:UNUSED_PAD src0_sel:DWORD src1_sel:BYTE_0
	s_sub_i32 s4, s0, s1
	v_cvt_f32_ubyte0_e32 v3, s3
	v_and_b32_e32 v1, 32, v1
	v_bfe_i32 v15, v0, 0, 16
	v_cvt_f32_i32_e32 v2, s4
	v_rcp_iflag_f32_e32 v4, v3
	v_add_u32_e32 v0, v1, v15
	v_lshlrev_b32_e32 v1, 3, v13
	v_and_b32_e32 v1, 0x1ffff0, v1
	v_add_lshl_u32 v1, v14, v1, 11
	v_lshl_add_u32 v130, v0, 1, v1
	v_mul_f32_e32 v0, v2, v4
	v_trunc_f32_e32 v0, v0
	v_fma_f32 v1, -v0, v3, v2
	v_cvt_i32_f32_e32 v0, v0
	s_ashr_i32 s0, s4, 30
	s_or_b32 s5, s0, 1
	v_cmp_ge_f32_e64 s[0:1], |v1|, v3
	s_and_b64 s[0:1], s[0:1], exec
	s_cselect_b32 s0, s5, 0
	v_readfirstlane_b32 s1, v0
	s_add_i32 s0, s1, s0
	s_sext_i32_i8 s1, s0
	s_mul_i32 s0, s0, s3
	s_sub_i32 s0, s4, s0
	s_sext_i32_i8 s0, s0
	s_add_i32 s4, s2, s0
	s_mov_b32 s2, 0x76543210
	s_lshl_b32 s0, s1, 2
	s_mov_b32 s3, 0xfedcba98
	s_lshr_b64 s[0:1], s[2:3], s0
	s_ashr_i32 s5, s4, 31
	s_lshl_b32 s1, s0, 19
	s_lshl_b64 s[6:7], s[4:5], 19
	s_and_b32 s1, s1, 0x780000
	v_readlane_b32 s8, v252, 19
	v_readlane_b32 s9, v252, 20
	s_add_u32 s22, s8, s1
	s_addc_u32 s23, s9, 0
	s_add_i32 s27, s86, 0x10000
	s_add_i32 s28, s86, 0x12000
	s_mov_b32 m0, s27
	s_add_u32 s20, s12, s6
	global_load_lds_dwordx4 v130, s[22:23]
	s_mov_b32 m0, s28
	s_addc_u32 s21, s13, s7
	s_add_i32 s29, s86, 0x2000
	global_load_lds_dwordx4 v128, s[22:23]
	s_mov_b32 m0, s86
	s_add_u32 s6, s22, 0x40000
	global_load_lds_dwordx4 v130, s[20:21]
	s_mov_b32 m0, s29
	s_addc_u32 s7, s23, 0
	s_add_i32 s30, s86, 0x14000
	global_load_lds_dwordx4 v128, s[20:21]
	s_mov_b32 m0, s30
	s_add_i32 s31, s86, 0x16000
	global_load_lds_dwordx4 v130, s[6:7]
	s_mov_b32 m0, s31
	v_mov_b32_e32 v133, 0
	global_load_lds_dwordx4 v128, s[6:7]
	s_add_u32 s6, s20, 0x40000
	s_addc_u32 s7, s21, 0
	s_add_i32 s33, s86, 0x4000
	s_mov_b32 m0, s33
	s_add_i32 s34, s86, 0x6000
	global_load_lds_dwordx4 v130, s[6:7]
	s_mov_b32 m0, s34
	v_mov_b32_e32 v131, v133
	global_load_lds_dwordx4 v128, s[6:7]
	v_readlane_b32 s6, v252, 61
	v_mov_b32_e32 v129, v133
	v_readlane_b32 s7, v252, 62
	s_mov_b32 s5, 0
	v_lshl_add_u64 v[6:7], s[22:23], 0, v[130:131]
	v_lshl_add_u64 v[4:5], s[22:23], 0, v[128:129]
	v_lshl_add_u64 v[0:1], s[20:21], 0, v[130:131]
	s_and_b64 vcc, exec, s[6:7]
	v_lshl_add_u64 v[2:3], s[20:21], 0, v[128:129]
	s_cbranch_vccnz .LBB0_979
	s_barrier
